# lever1: attention item loop - the per-item sink value read by s_load instead of global_load, so the vmcnt(0) in the softmax no longer drains the next item's 14 prefetch loads (they overlap softmax and
# baseline (speedup 1.0000x reference)
.LBB0_67:
	s_and_b32 s28, s40, 3
	s_lshl_b32 s29, s28, 2
	s_add_i32 s42, s29, s36
	s_add_i32 s29, s42, 1
	v_cvt_f32_i32_e32 v156, s29
	v_lshl_add_u32 v158, s41, 6, v204
	v_cvt_f32_i32_e32 v158, v158
	v_mul_f32_e32 v157, -0.5, v156
	v_cmp_gt_f32_e32 vcc, s57, v157
	s_and_b64 s[44:45], vcc, exec
	s_cselect_b32 s29, 0xffffffc0, 0
	s_ashr_i32 s43, s42, 31
	s_lshl_b64 s[42:43], s[42:43], 2
	v_cndmask_b32_e32 v157, 0, v215, vcc
	s_add_u32 s42, s33, s42
	v_fmac_f32_e32 v157, -0.5, v156
	s_addc_u32 s43, s35, s43
	v_exp_f32_e32 v156, v157
	s_load_dword s42, s[42:43], 0x0
	s_and_b64 vcc, exec, s[8:9]
	v_ldexp_f32 v156, v156, s29
	v_mul_f32_e32 v156, 0x3fb8aa3b, v156
	v_add_f32_e32 v159, -1.0, v158
	v_fma_f32 v81, -v156, |v159|, v81
	v_add_f32_e32 v159, -2.0, v158
	v_fma_f32 v82, -v156, |v159|, v82
	v_add_f32_e32 v159, 0xc0400000, v158
	v_fma_f32 v83, -v156, |v159|, v83
	v_add_f32_e32 v159, 0xc1000000, v158
	v_fma_f32 v84, -v156, |v159|, v84
	v_add_f32_e32 v159, 0xc1100000, v158
	v_fma_f32 v85, -v156, |v159|, v85
	v_add_f32_e32 v159, 0xc1200000, v158
	v_fma_f32 v86, -v156, |v159|, v86
	v_add_f32_e32 v159, 0xc1300000, v158
	v_fma_f32 v87, -v156, |v159|, v87
	v_add_f32_e32 v159, 0xc1800000, v158
	v_fma_f32 v88, -v156, |v159|, v88
	v_add_f32_e32 v159, 0xc1880000, v158
	v_fma_f32 v89, -v156, |v159|, v89
	v_add_f32_e32 v159, 0xc1900000, v158
	v_fma_f32 v90, -v156, |v159|, v90
	v_add_f32_e32 v159, 0xc1980000, v158
	v_fma_f32 v91, -v156, |v159|, v91
	v_add_f32_e32 v159, 0xc1c00000, v158
	v_fma_f32 v92, -v156, |v159|, v92
	v_add_f32_e32 v159, 0xc1c80000, v158
	v_fma_f32 v93, -v156, |v159|, v93
	v_add_f32_e32 v159, 0xc1d00000, v158
	v_add_f32_e32 v160, 0xc2000000, v158
	v_fma_f32 v80, -v156, |v158|, v80
	v_fma_f32 v94, -v156, |v159|, v94
	v_add_f32_e32 v159, 0xc1d80000, v158
	v_fma_f32 v64, -v156, |v160|, v64
	v_add_f32_e32 v160, 0xc2040000, v158
	v_fma_f32 v95, -v156, |v159|, v95
	v_fma_f32 v65, -v156, |v160|, v65
	v_add_f32_e32 v160, 0xc2080000, v158
	v_fma_f32 v66, -v156, |v160|, v66
	v_add_f32_e32 v160, 0xc20c0000, v158
	v_fma_f32 v67, -v156, |v160|, v67
	v_add_f32_e32 v160, 0xc2200000, v158
	v_fma_f32 v68, -v156, |v160|, v68
	v_add_f32_e32 v160, 0xc2240000, v158
	v_fma_f32 v69, -v156, |v160|, v69
	v_add_f32_e32 v160, 0xc2280000, v158
	v_fma_f32 v70, -v156, |v160|, v70
	v_add_f32_e32 v160, 0xc22c0000, v158
	v_fma_f32 v71, -v156, |v160|, v71
	v_add_f32_e32 v160, 0xc2400000, v158
	v_fma_f32 v72, -v156, |v160|, v72
	v_add_f32_e32 v160, 0xc2440000, v158
	v_fma_f32 v73, -v156, |v160|, v73
	v_add_f32_e32 v160, 0xc2480000, v158
	v_fma_f32 v74, -v156, |v160|, v74
	v_add_f32_e32 v160, 0xc24c0000, v158
	v_fma_f32 v75, -v156, |v160|, v75
	v_add_f32_e32 v160, 0xc2600000, v158
	v_fma_f32 v76, -v156, |v160|, v76
	v_add_f32_e32 v160, 0xc2640000, v158
	v_fma_f32 v77, -v156, |v160|, v77
	v_add_f32_e32 v160, 0xc2680000, v158
	v_fma_f32 v78, -v156, |v160|, v78
	v_add_f32_e32 v160, 0xc26c0000, v158
	v_fma_f32 v79, -v156, |v160|, v79
	s_waitcnt lgkmcnt(0)
	v_mov_b32_e32 v157, s42
	v_mul_f32_e32 v157, 0x3fb8aa3b, v157
	v_max3_f32 v159, v157, v80, v81
	v_max3_f32 v159, v159, v82, v83
	v_max3_f32 v159, v159, v84, v85
	v_max3_f32 v159, v159, v86, v87
	v_max3_f32 v159, v159, v88, v89
	v_max3_f32 v159, v159, v90, v91
	v_max3_f32 v159, v159, v92, v93
	v_max3_f32 v159, v159, v94, v95
	v_max3_f32 v159, v159, v64, v65
	v_max3_f32 v159, v159, v66, v67
	v_max3_f32 v159, v159, v68, v69
	v_max3_f32 v159, v159, v70, v71
	v_max3_f32 v159, v159, v72, v73
	v_max3_f32 v159, v159, v74, v75
	v_max3_f32 v159, v159, v76, v77
	v_max3_f32 v160, v159, v78, v79
	s_cbranch_vccnz .LBB0_69
	v_pk_add_f32 v[162:163], v[158:159], s[68:69] op_sel_hi:[0,1]
	v_and_b32_e32 v163, 0x7fffffff, v163
	v_and_b32_e32 v162, 0x7fffffff, v162
	v_pk_fma_f32 v[48:49], v[156:157], v[162:163], v[48:49] op_sel_hi:[0,1,1] neg_lo:[1,0,0] neg_hi:[1,0,0]
	v_max3_f32 v159, v160, v48, v49
	v_pk_add_f32 v[160:161], v[158:159], s[70:71] op_sel_hi:[0,1]
	v_and_b32_e32 v161, 0x7fffffff, v161
	v_and_b32_e32 v160, 0x7fffffff, v160
	v_pk_fma_f32 v[50:51], v[156:157], v[160:161], v[50:51] op_sel_hi:[0,1,1] neg_lo:[1,0,0] neg_hi:[1,0,0]
	s_mov_b32 s42, 0xc2900000
	v_max3_f32 v159, v159, v50, v51
	s_mov_b32 s43, 0xc2920000
	v_pk_add_f32 v[160:161], v[158:159], s[42:43] op_sel_hi:[0,1]
	v_and_b32_e32 v161, 0x7fffffff, v161
	v_and_b32_e32 v160, 0x7fffffff, v160
	v_pk_fma_f32 v[52:53], v[156:157], v[160:161], v[52:53] op_sel_hi:[0,1,1] neg_lo:[1,0,0] neg_hi:[1,0,0]
	s_mov_b32 s42, 0xc2940000
	v_max3_f32 v159, v159, v52, v53
	s_mov_b32 s43, 0xc2960000
	v_pk_add_f32 v[160:161], v[158:159], s[42:43] op_sel_hi:[0,1]
	v_and_b32_e32 v161, 0x7fffffff, v161
	v_and_b32_e32 v160, 0x7fffffff, v160
	v_pk_fma_f32 v[54:55], v[156:157], v[160:161], v[54:55] op_sel_hi:[0,1,1] neg_lo:[1,0,0] neg_hi:[1,0,0]
	s_mov_b32 s42, 0xc2a00000
	v_max3_f32 v159, v159, v54, v55
	s_mov_b32 s43, 0xc2a20000
	v_pk_add_f32 v[160:161], v[158:159], s[42:43] op_sel_hi:[0,1]
	v_and_b32_e32 v161, 0x7fffffff, v161
	v_and_b32_e32 v160, 0x7fffffff, v160
	v_pk_fma_f32 v[56:57], v[156:157], v[160:161], v[56:57] op_sel_hi:[0,1,1] neg_lo:[1,0,0] neg_hi:[1,0,0]
	s_mov_b32 s42, 0xc2a40000
	v_max3_f32 v159, v159, v56, v57
	s_mov_b32 s43, 0xc2a60000
	v_pk_add_f32 v[160:161], v[158:159], s[42:43] op_sel_hi:[0,1]
	v_and_b32_e32 v161, 0x7fffffff, v161
	v_and_b32_e32 v160, 0x7fffffff, v160
	v_pk_fma_f32 v[58:59], v[156:157], v[160:161], v[58:59] op_sel_hi:[0,1,1] neg_lo:[1,0,0] neg_hi:[1,0,0]
	s_mov_b32 s42, 0xc2b00000
	v_max3_f32 v159, v159, v58, v59
	s_mov_b32 s43, 0xc2b20000
	v_pk_add_f32 v[160:161], v[158:159], s[42:43] op_sel_hi:[0,1]
	v_and_b32_e32 v161, 0x7fffffff, v161
	v_and_b32_e32 v160, 0x7fffffff, v160
	v_pk_fma_f32 v[60:61], v[156:157], v[160:161], v[60:61] op_sel_hi:[0,1,1] neg_lo:[1,0,0] neg_hi:[1,0,0]
	s_mov_b32 s42, 0xc2b40000
	v_max3_f32 v159, v159, v60, v61
	s_mov_b32 s43, 0xc2b60000
	v_pk_add_f32 v[160:161], v[158:159], s[42:43] op_sel_hi:[0,1]
	v_and_b32_e32 v161, 0x7fffffff, v161
	v_and_b32_e32 v160, 0x7fffffff, v160
	v_pk_fma_f32 v[62:63], v[156:157], v[160:161], v[62:63] op_sel_hi:[0,1,1] neg_lo:[1,0,0] neg_hi:[1,0,0]
	v_max3_f32 v160, v159, v62, v63
